# attention leading-half DMA pieces: scalar setup in front of the gap's VALU ops, LDS-DMA instruction behind them (no s_nop pad)
# speedup vs baseline: 1.0119x; 1.0010x over previous
.LqL_ldsb:
	s_add_i32 s33, s65, 0x10000
	s_and_b32 s33, s33, 0x18000
	s_add_i32 s33, s57, s33
	v_lshlrev_b32_e32 v198, 1, v150
	v_mfma_f32_32x32x16_bf16 v[32:47], v[242:245], v[64:67], v[32:47]
	s_mov_b32 m0, s33
	v_exp_f32_e32 v72, v72
	v_exp_f32_e32 v73, v73
	v_exp_f32_e32 v74, v74
	v_exp_f32_e32 v75, v75
	v_add_f32_e32 v184, v72, v73
	s_and_b32 s100, s65, 0x18000
	v_add_u32_e32 v194, s100, v149
	v_add_u32_e32 v195, v194, v157
	v_add_u32_e32 v196, v194, v193
	global_load_lds_dwordx4 v188, s[70:71]
	v_mfma_f32_32x32x16_bf16 v[48:63], v[246:249], v[64:67], v[48:63]
	v_exp_f32_e32 v76, v76
	v_exp_f32_e32 v77, v77
	v_cvt_pk_bf16_f32 v68, v72, v73
	v_add_f32_e32 v185, v74, v75
	v_cvt_pk_bf16_f32 v69, v74, v75
	v_add_u32_e32 v197, v194, v208
	v_add_u32_e32 v194, v194, v209
	ds_read_b128 v[132:135], v195
	ds_read_b128 v[116:119], v195 offset:4096
	v_mfma_f32_32x32x16_bf16 v[16:31], v[250:253], v[64:67], v[16:31]
	s_add_u32 s100, s70, 0x40000
	s_addc_u32 s101, s71, 0
	s_add_i32 m0, s33, 0x2000
	v_exp_f32_e32 v78, v78
	v_exp_f32_e32 v79, v79
	v_add_f32_e32 v186, v76, v77
	v_cvt_pk_bf16_f32 v70, v76, v77
	v_add_f32_e32 v184, v184, v185
	ds_read_b128 v[136:139], v196
	ds_read_b128 v[120:123], v196 offset:4096
	ds_read_b128 v[140:143], v197
	ds_read_b128 v[124:127], v197 offset:4096
	global_load_lds_dwordx4 v188, s[100:101]
	v_mfma_f32_32x32x16_bf16 v[0:15], v[200:203], v[64:67], v[0:15]
	v_add_f32_e32 v187, v78, v79
	v_cvt_pk_bf16_f32 v71, v78, v79
	v_add_f32_e32 v186, v186, v187
	v_add_f32_e32 v184, v184, v186
	v_add_f32_e32 v206, v206, v184
	ds_read_b128 v[128:131], v194
	ds_read_b128 v[112:115], v194 offset:4096
	ds_read_b128 v[242:245], v218 offset:16384
	ds_read_b128 v[246:249], v218 offset:20480
	ds_read_b128 v[250:253], v218 offset:24576
	ds_read_b128 v[200:203], v218 offset:28672
	v_mfma_f32_32x32x16_bf16 v[32:47], v[220:223], v[68:71], v[32:47]
	s_add_i32 m0, s33, 0x4000
	v_exp_f32_e32 v80, v80
	v_exp_f32_e32 v81, v81
	v_exp_f32_e32 v82, v82
	v_exp_f32_e32 v83, v83
	v_add_f32_e32 v184, v80, v81
	global_load_lds_dwordx4 v198, s[66:67]
	v_mfma_f32_32x32x16_bf16 v[48:63], v[224:227], v[68:71], v[48:63]
	v_exp_f32_e32 v84, v84
	v_exp_f32_e32 v85, v85
	v_cvt_pk_bf16_f32 v72, v80, v81
	v_add_f32_e32 v185, v82, v83
	v_cvt_pk_bf16_f32 v73, v82, v83
	v_mfma_f32_32x32x16_bf16 v[16:31], v[234:237], v[68:71], v[16:31]
	s_add_u32 s100, s66, 0x40000
	s_addc_u32 s101, s67, 0
	s_add_i32 m0, s33, 0x6000
	v_exp_f32_e32 v86, v86
	v_exp_f32_e32 v87, v87
	v_add_f32_e32 v186, v84, v85
	v_cvt_pk_bf16_f32 v74, v84, v85
	v_add_f32_e32 v184, v184, v185
	global_load_lds_dwordx4 v198, s[100:101]
	v_mfma_f32_32x32x16_bf16 v[0:15], v[238:241], v[68:71], v[0:15]
	v_add_f32_e32 v187, v86, v87
	v_cvt_pk_bf16_f32 v75, v86, v87
	v_add_f32_e32 v186, v186, v187
	v_add_f32_e32 v184, v184, v186
	v_add_f32_e32 v206, v206, v184
	ds_read_b128 v[220:223], v219 offset:16384
	ds_read_b128 v[224:227], v219 offset:20480
	ds_read_b128 v[234:237], v219 offset:24576
	ds_read_b128 v[238:241], v219 offset:28672
	s_waitcnt lgkmcnt(4)
	v_mfma_f32_32x32x16_bf16 v[32:47], v[242:245], v[72:75], v[32:47]
	s_add_u32 s100, s70, 0x1000
	s_addc_u32 s101, s71, 0
	s_add_i32 m0, s33, 0x1000
	v_exp_f32_e32 v88, v88
	v_exp_f32_e32 v89, v89
	v_exp_f32_e32 v90, v90
	v_exp_f32_e32 v91, v91
	v_add_f32_e32 v184, v88, v89
	global_load_lds_dwordx4 v188, s[100:101]
	v_mfma_f32_32x32x16_bf16 v[48:63], v[246:249], v[72:75], v[48:63]
	v_exp_f32_e32 v92, v92
	v_exp_f32_e32 v93, v93
	v_cvt_pk_bf16_f32 v76, v88, v89
	v_add_f32_e32 v185, v90, v91
	v_cvt_pk_bf16_f32 v77, v90, v91
	v_mfma_f32_32x32x16_bf16 v[16:31], v[250:253], v[72:75], v[16:31]
	s_add_u32 s100, s70, 0x41000
	s_addc_u32 s101, s71, 0
	s_add_i32 m0, s33, 0x3000
	v_exp_f32_e32 v94, v94
	v_exp_f32_e32 v95, v95
	v_add_f32_e32 v186, v92, v93
	v_cvt_pk_bf16_f32 v78, v92, v93
	v_add_f32_e32 v184, v184, v185
	global_load_lds_dwordx4 v188, s[100:101]
	v_mfma_f32_32x32x16_bf16 v[0:15], v[200:203], v[72:75], v[0:15]
	v_add_f32_e32 v187, v94, v95
	v_cvt_pk_bf16_f32 v79, v94, v95
	v_add_f32_e32 v186, v186, v187
	v_add_f32_e32 v184, v184, v186
	v_add_f32_e32 v206, v206, v184
	s_waitcnt lgkmcnt(0)
	v_mfma_f32_32x32x16_bf16 v[32:47], v[220:223], v[76:79], v[32:47]
	s_add_u32 s100, s66, 0x20000
	s_addc_u32 s101, s67, 0
	s_add_i32 m0, s33, 0x5000
	s_nop 0
	global_load_lds_dwordx4 v198, s[100:101]
	v_mfma_f32_32x32x16_bf16 v[48:63], v[224:227], v[76:79], v[48:63]
	s_add_u32 s100, s66, 0x60000
	s_addc_u32 s101, s67, 0
	s_add_i32 m0, s33, 0x7000
	s_nop 0
	global_load_lds_dwordx4 v198, s[100:101]
	s_waitcnt lgkmcnt(0)
	s_barrier
	s_add_i32 s65, s65, 0x8000
	s_addk_i32 s23, 0x100
	s_add_i32 s36, s36, 64
	s_mov_b32 s33, s54
	s_setprio 0
	s_cmpk_eq_i32 s23, 0x1e00
	v_mfma_f32_32x32x16_bf16 v[16:31], v[234:237], v[76:79], v[16:31]
	v_mfma_f32_32x32x16_bf16 v[0:15], v[238:241], v[76:79], v[0:15]
	s_cbranch_scc0 .LqL_top
	s_branch .LBB0_284
